# scan phase: y partials stored as [token][wave][row][16 quads], helper y-out = 4 tokens x 16 rows per wave with ds_read_b128; scanner LDS prefetch 2 steps ahead with one wait per step
# baseline (speedup 1.0000x reference)
.LBB0_1332:
	s_or_b64 exec, exec, s[4:5]
	v_lshlrev_b32_e32 v3, 16, v5
	v_mul_f32_e32 v3, 0xbfb8aa3b, v3
	v_exp_f32_e32 v5, v3
	s_waitcnt vmcnt(2)
	v_lshlrev_b32_e32 v3, 16, v8
	v_mul_f32_e32 v8, v25, v3
	v_lshlrev_b32_e32 v17, 16, v7
	v_mul_f32_e32 v7, v8, v8
	s_nop 1
	v_add_f32_dpp v7, v7, v7 row_ror:1 row_mask:0xf bank_mask:0xf
	v_add_f32_e32 v5, 1.0, v5
	s_nop 1
	v_add_f32_dpp v7, v7, v7 row_ror:2 row_mask:0xf bank_mask:0xf
	v_rcp_f32_e32 v5, v5
	s_nop 1
	v_add_f32_dpp v7, v7, v7 row_ror:4 row_mask:0xf bank_mask:0xf
	s_nop 0
	s_nop 1
	v_add_f32_dpp v7, v7, v7 row_ror:8 row_mask:0xf bank_mask:0xf
	v_mul_f32_e32 v5, 0xbf1b4598, v5
	v_mov_b32_e32 v9, v7
	s_nop 1
	v_permlane16_swap_b32_e32 v7, v9
	v_add_f32_e32 v7, v7, v9
	v_mov_b32_e32 v9, v7
	s_nop 1
	v_permlane32_swap_b32_e32 v7, v9
	v_add_f32_e32 v7, v7, v9
	v_mul_f32_e32 v9, 0x4f800000, v7
	v_cmp_gt_f32_e32 vcc, s35, v7
	v_mul_f32_e32 v5, 0x3fb8aa3b, v5
	v_exp_f32_e32 v14, v5
	v_cndmask_b32_e32 v7, v7, v9, vcc
	v_sqrt_f32_e32 v9, v7
	s_mov_b32 s35, 0
	v_add_u32_e32 v5, -1, v9
	v_fma_f32 v11, -v5, v9, v7
	v_cmp_ge_f32_e64 s[4:5], 0, v11
	v_add_u32_e32 v11, 1, v9
	s_nop 0
	v_cndmask_b32_e64 v5, v9, v5, s[4:5]
	v_fma_f32 v9, -v11, v9, v7
	v_cmp_lt_f32_e64 s[4:5], 0, v9
	s_nop 1
	v_cndmask_b32_e64 v5, v5, v11, s[4:5]
	v_mul_f32_e32 v9, 0x37800000, v5
	v_cndmask_b32_e32 v5, v5, v9, vcc
	v_cmp_class_f32_e32 vcc, v7, v2
	s_nop 1
	v_cndmask_b32_e32 v2, v5, v7, vcc
	v_min_f32_e64 v2, -v2, s40
	v_rcp_f32_e32 v5, v2
	s_waitcnt vmcnt(0)
	v_lshlrev_b32_e32 v2, 16, v6
	v_add_f32_e32 v6, -1.0, v2
	v_fma_f32 v7, v26, v6, 1.0
	v_mul_f32_e32 v5, v8, v5
	v_xor_b32_e32 v6, 0x80000000, v5
	v_pk_mul_f32 v[2:3], v[6:7], v[2:3]
	s_nop 0
	v_mov_b32_e32 v15, v2
	v_mov_b32_e32 v16, v3
	v_add_u32_e32 v2, 0x10b00, v12
	ds_write_b128 v28, v[14:17] offset:7168
	ds_write_b32 v2, v5
	s_and_saveexec_b64 s[4:5], s[2:3]
	v_lshlrev_b32_e32 v2, 16, v4
	ds_write_b32 v10, v2 offset:448
	s_or_b64 exec, exec, s[4:5]
	s_lshl_b32 s53, s39, 13
	s_or_b32 s51, s30, 1
	s_or_b32 s49, s30, 2
	s_or_b32 s47, s30, 3
	s_or_b32 s45, s30, 4
	s_or_b32 s43, s30, 5
	s_or_b32 s41, s30, 6
	s_or_b32 s39, s30, 7
	s_lshl_b32 s52, s51, 10
	s_lshl_b32 s50, s49, 10
	s_lshl_b32 s48, s47, 10
	s_lshl_b32 s46, s45, 10
	s_lshl_b32 s44, s43, 10
	s_lshl_b32 s42, s41, 10
	s_lshl_b32 s40, s39, 10
	s_add_u32 s4, s36, 32
	s_addc_u32 s5, s37, 0
	v_mov_b32_e32 v2, 0x1800
	s_mul_i32 s54, s5, 0x1800
	v_mad_u64_u32 v[0:1], s[36:37], s4, v2, v[0:1]
	s_lshl_b64 s[4:5], s[4:5], 10
	s_movk_i32 s36, 0x1000
	v_lshl_add_u64 v[4:5], s[4:5], 0, v[22:23]
	v_add_u32_e32 v1, s54, v1
	v_add_co_u32_e32 v2, vcc, s36, v0
	v_lshlrev_b64 v[4:5], 1, v[4:5]
	s_nop 0
	v_addc_co_u32_e32 v3, vcc, 0, v1, vcc
	v_lshl_add_u64 v[6:7], s[12:13], 0, v[4:5]
	s_movk_i32 s36, 0x2000
	global_load_ushort v16, v[6:7], off
	global_load_ushort v17, v[2:3], off
	global_load_ushort v18, v[2:3], off offset:2048
	v_add_co_u32_e32 v2, vcc, s36, v0
	v_lshl_add_u64 v[6:7], s[10:11], 0, v[4:5]
	s_mov_b64 s[4:5], 0x1800
	v_addc_co_u32_e32 v3, vcc, 0, v1, vcc
	s_mov_b64 s[36:37], 0x800
	v_lshl_add_u64 v[8:9], v[0:1], 0, s[4:5]
	global_load_ushort v21, v[6:7], off
	global_load_ushort v19, v[8:9], off offset:2048
	global_load_ushort v30, v[2:3], off offset:2048
	v_lshl_add_u64 v[2:3], v[4:5], 0, s[36:37]
	v_lshl_add_u64 v[6:7], s[12:13], 0, v[2:3]
	s_mov_b64 s[36:37], 0x3000
	s_movk_i32 s54, 0x4000
	global_load_ushort v31, v[6:7], off
	v_lshl_add_u64 v[6:7], v[0:1], 0, s[36:37]
	v_add_co_u32_e32 v8, vcc, s54, v0
	s_mov_b64 s[56:57], 0x1000
	s_nop 0
	v_addc_co_u32_e32 v9, vcc, 0, v1, vcc
	global_load_ushort v32, v[6:7], off offset:2048
	v_lshl_add_u64 v[6:7], v[4:5], 0, s[56:57]
	s_movk_i32 s54, 0x5000
	v_lshl_add_u64 v[10:11], s[12:13], 0, v[6:7]
	v_lshl_add_u64 v[6:7], s[10:11], 0, v[6:7]
	s_mov_b64 s[56:57], 0x4800
	v_add_co_u32_e32 v12, vcc, s54, v0
	global_load_ushort v33, v[10:11], off
	v_lshl_add_u64 v[10:11], v[0:1], 0, s[56:57]
	v_addc_co_u32_e32 v13, vcc, 0, v1, vcc
	global_load_ushort v34, v[6:7], off
	global_load_ushort v35, v[10:11], off offset:2048
	global_load_ushort v36, v[12:13], off offset:2048
	v_lshl_add_u64 v[6:7], v[4:5], 0, s[4:5]
	v_lshl_add_u64 v[10:11], s[12:13], 0, v[6:7]
	s_mov_b64 s[4:5], 0x6000
	global_load_ushort v37, v[10:11], off
	v_lshl_add_u64 v[10:11], v[0:1], 0, s[4:5]
	s_movk_i32 s4, 0x7000
	v_lshl_add_u64 v[6:7], s[10:11], 0, v[6:7]
	v_add_co_u32_e32 v12, vcc, s4, v0
	s_mov_b64 s[4:5], 0x2000
	s_nop 0
	v_addc_co_u32_e32 v13, vcc, 0, v1, vcc
	global_load_ushort v38, v[6:7], off
	global_load_ushort v39, v[10:11], off offset:2048
	global_load_ushort v40, v[0:1], off
	global_load_ushort v41, v[0:1], off offset:2048
	global_load_ushort v42, v[8:9], off offset:-4096
	global_load_ushort v43, v[8:9], off
	global_load_ushort v44, v[8:9], off offset:2048
	global_load_ushort v45, v[12:13], off offset:-4096
	global_load_ushort v46, v[12:13], off
	v_lshl_add_u64 v[6:7], v[4:5], 0, s[4:5]
	v_lshl_add_u64 v[8:9], s[12:13], 0, v[6:7]
	s_mov_b64 s[4:5], 0x7800
	global_load_ushort v47, v[8:9], off
	v_lshl_add_u64 v[8:9], v[0:1], 0, s[4:5]
	s_mov_b32 s4, 0x8000
	v_lshl_add_u64 v[6:7], s[10:11], 0, v[6:7]
	v_add_co_u32_e32 v10, vcc, s4, v0
	s_mov_b64 s[4:5], 0x2800
	s_nop 0
	v_addc_co_u32_e32 v11, vcc, 0, v1, vcc
	global_load_ushort v48, v[6:7], off
	global_load_ushort v49, v[8:9], off offset:2048
	global_load_ushort v50, v[10:11], off offset:2048
	v_lshl_add_u64 v[6:7], v[4:5], 0, s[4:5]
	v_lshl_add_u64 v[8:9], s[12:13], 0, v[6:7]
	s_mov_b64 s[4:5], 0x9000
	global_load_ushort v51, v[8:9], off
	v_lshl_add_u64 v[8:9], v[0:1], 0, s[4:5]
	s_mov_b32 s4, 0xa000
	global_load_ushort v52, v[8:9], off offset:2048
	v_lshl_add_u64 v[8:9], v[4:5], 0, s[36:37]
	v_add_co_u32_e32 v10, vcc, s4, v0
	v_lshl_add_u64 v[14:15], s[12:13], 0, v[8:9]
	s_mov_b64 s[4:5], 0xa800
	v_addc_co_u32_e32 v11, vcc, 0, v1, vcc
	global_load_ushort v53, v[14:15], off
	v_lshl_add_u64 v[14:15], v[0:1], 0, s[4:5]
	s_mov_b32 s4, 0xb000
	v_add_co_u32_e32 v0, vcc, s4, v0
	s_mov_b64 s[4:5], 0x3800
	s_nop 0
	v_addc_co_u32_e32 v1, vcc, 0, v1, vcc
	global_load_ushort v12, v[12:13], off offset:2048
	s_nop 0
	global_load_ushort v13, v[10:11], off offset:-4096
	global_load_ushort v54, v[10:11], off
	s_nop 0
	global_load_ushort v10, v[10:11], off offset:2048
	s_nop 0
	global_load_ushort v11, v[14:15], off offset:2048
	v_lshl_add_u64 v[6:7], s[10:11], 0, v[6:7]
	global_load_ushort v14, v[0:1], off offset:2048
	v_lshl_add_u64 v[0:1], v[4:5], 0, s[4:5]
	v_lshl_add_u64 v[4:5], s[12:13], 0, v[0:1]
	global_load_ushort v15, v[4:5], off
	v_lshl_add_u64 v[4:5], s[10:11], 0, v[8:9]
	v_lshl_add_u64 v[0:1], s[10:11], 0, v[0:1]
	global_load_ushort v55, v[4:5], off
	global_load_ushort v56, v[0:1], off
	global_load_ushort v57, v[6:7], off
	v_lshl_add_u64 v[0:1], s[10:11], 0, v[2:3]
	global_load_ushort v58, v[0:1], off
	s_mov_b32 s54, 0x5040100
	s_add_i32 s4, 0, 0x15540
	s_lshl_b32 s10, s55, 1
	s_add_u32 s10, s14, s10
	s_addc_u32 s11, s15, 0
	s_lshl_b32 s34, s34, 5
	s_add_u32 s10, s10, s34
	s_addc_u32 s11, s11, 0
	s_lshl_b64 s[36:37], s[30:31], 11
	v_lshlrev_b64 v[22:23], 1, v[22:23]
	s_movk_i32 s31, 0x800
	s_movk_i32 s55, 0xe000
	s_mov_b32 s56, 0xf800000
	s_mov_b32 s57, 0xab8cbccc
	s_mov_b32 s58, 0
	s_waitcnt vmcnt(29)
	v_perm_b32 v7, v35, v32, s54
	v_mov_b32_e32 v35, 0
	s_waitcnt vmcnt(24)
	v_perm_b32 v0, v18, v40, s54
	s_waitcnt vmcnt(23)
	v_perm_b32 v6, v19, v41, s54
	v_perm_b32 v19, v38, v34, s54
	v_and_b32_e32 v34, 3, v24
	v_lshlrev_b32_e32 v32, 2, v34
	v_lshlrev_b32_e32 v34, 1, v34
	s_waitcnt vmcnt(20)
	v_perm_b32 v1, v44, v42, s54
	s_waitcnt vmcnt(15)
	v_perm_b32 v4, v49, v39, s54
	s_waitcnt vmcnt(14)
	v_perm_b32 v8, v50, v46, s54
	s_waitcnt vmcnt(10)
	v_perm_b32 v2, v12, v45, s54
	v_perm_b32 v12, v51, v47, s54
	s_waitcnt vmcnt(7)
	v_perm_b32 v3, v10, v13, s54
	v_perm_b32 v10, v30, v17, s54
	v_lshlrev_b32_e32 v30, 8, v20
	s_waitcnt vmcnt(5)
	v_perm_b32 v9, v14, v54, s54
	v_perm_b32 v14, v31, v16, s54
	v_lshlrev_b32_e32 v31, 2, v24
	v_and_b32_e32 v31, 48, v31
	v_lshlrev_b32_e32 v31, 2, v31
	s_waitcnt vmcnt(4)
	v_perm_b32 v13, v15, v53, s54
	v_perm_b32 v15, v37, v33, s54
	v_lshlrev_b32_e32 v20, 2, v20
	v_perm_b32 v5, v11, v52, s54
	s_waitcnt vmcnt(0)
	v_perm_b32 v18, v58, v21, s54
	v_add_u32_e32 v21, s4, v30
	v_add3_u32 v33, v21, v31, v32
	v_and_b32_e32 v21, 12, v24
	v_cmp_eq_u32_e64 s[4:5], 0, v21
	v_ashrrev_i32_e32 v21, 31, v20
	v_lshl_add_u64 v[20:21], v[20:21], 1, s[10:11]
	v_lshl_add_u64 v[20:21], v[20:21], 0, v[34:35]
	s_mov_b64 s[10:11], 0x4800000
	v_lshl_add_u64 v[20:21], v[20:21], 0, s[10:11]
	s_lshl_b64 s[10:11], s[6:7], 24
	s_add_u32 s7, s10, s36
	s_addc_u32 s10, s11, s37
	s_add_u32 s12, s12, s7
	s_addc_u32 s13, s13, s10
	s_add_u32 s36, s14, s7
	s_addc_u32 s37, s15, s10
	s_mul_hi_i32 s7, s6, 0x3000000
	s_mul_i32 s6, s6, 0x3000000
	s_mul_i32 s11, s30, 0x1800
	s_mul_hi_u32 s10, s30, 0x1800
	s_add_u32 s6, s6, s11
	s_addc_u32 s7, s7, s10
	s_add_u32 s14, s14, s6
	v_perm_b32 v11, v36, v43, s54
	v_perm_b32 v17, v56, v55, s54
	v_perm_b32 v16, v57, v48, s54
	s_addc_u32 s15, s15, s7
	v_mov_b32_e32 v34, 0x260
	v_lshrrev_b32_e32 v132, 4, v24
	v_and_b32_e32 v133, 15, v24
	v_lshlrev_b32_e32 v132, 10, v132
	v_lshl_add_u32 v132, v133, 6, v132
	v_add_u32_e32 v132, s53, v132
	v_add_u32_e32 v132, 0x15540, v132
	v_and_b32_e32 v136, 15, v24
	v_and_b32_e32 v137, 3, v24
	v_sub_u32_e32 v136, v136, v137
	v_lshlrev_b32_e32 v136, 1, v136
	v_lshrrev_b32_e32 v137, 4, v24
	v_mul_u32_u24_e32 v137, 0x7f8, v137
	v_add_u32_e32 v136, v136, v137
	v_mov_b32_e32 v137, 0
	v_lshl_add_u64 v[134:135], v[20:21], 0, v[136:137]
	s_branch .LBB0_1337

.LBB0_1357:
	s_and_b64 vcc, exec, s[6:7]
	s_cbranch_vccz .LBB0_1336
	s_and_b32 s6, s55, 0x2000
	v_lshl_add_u32 v35, s6, 2, v132
	ds_read_b128 v[140:143], v35
	ds_read_b128 v[144:147], v35 offset:16
	ds_read_b128 v[148:151], v35 offset:32
	ds_read_b128 v[152:155], v35 offset:48
	ds_read_b128 v[156:159], v35 offset:4096
	ds_read_b128 v[160:163], v35 offset:4112
	ds_read_b128 v[164:167], v35 offset:4128
	ds_read_b128 v[168:171], v35 offset:4144
	s_add_i32 s34, s58, -1
	s_lshl_b64 s[6:7], s[34:35], 5
	s_add_u32 s10, s6, s18
	s_addc_u32 s11, s7, s19
	s_add_u32 s60, s10, s30
	s_addc_u32 s61, s11, 0
	s_lshl_b64 s[60:61], s[60:61], 11
	v_lshl_add_u64 v[36:37], v[134:135], 0, s[60:61]
	s_add_u32 s60, s60, 0x2000
	s_addc_u32 s61, s61, 0
	v_lshl_add_u64 v[38:39], v[134:135], 0, s[60:61]
	s_waitcnt lgkmcnt(4)
	v_add_f32_e32 v140, v140, v141
	v_add_f32_e32 v142, v142, v143
	v_add_f32_e32 v144, v144, v145
	v_add_f32_e32 v146, v146, v147
	v_add_f32_e32 v148, v148, v149
	v_add_f32_e32 v150, v150, v151
	v_add_f32_e32 v152, v152, v153
	v_add_f32_e32 v154, v154, v155
	v_add_f32_e32 v140, v140, v142
	v_add_f32_e32 v144, v144, v146
	v_add_f32_e32 v148, v148, v150
	v_add_f32_e32 v152, v152, v154
	v_add_f32_e32 v140, v140, v144
	v_add_f32_e32 v148, v148, v152
	v_add_f32_e32 v140, v140, v148
	v_cvt_pk_bf16_f32 v140, v140, s0
	global_store_short v[36:37], v140, off
	s_waitcnt lgkmcnt(0)
	v_add_f32_e32 v156, v156, v157
	v_add_f32_e32 v158, v158, v159
	v_add_f32_e32 v160, v160, v161
	v_add_f32_e32 v162, v162, v163
	v_add_f32_e32 v164, v164, v165
	v_add_f32_e32 v166, v166, v167
	v_add_f32_e32 v168, v168, v169
	v_add_f32_e32 v170, v170, v171
	v_add_f32_e32 v156, v156, v158
	v_add_f32_e32 v160, v160, v162
	v_add_f32_e32 v164, v164, v166
	v_add_f32_e32 v168, v168, v170
	v_add_f32_e32 v156, v156, v160
	v_add_f32_e32 v164, v164, v168
	v_add_f32_e32 v156, v156, v164
	v_cvt_pk_bf16_f32 v156, v156, s0
	global_store_short v[38:39], v156, off
	s_branch .LBB0_1336
.LBB0_1374:
	v_add_u32_e32 v0, 0x8000, v132
	s_waitcnt lgkmcnt(0)
	s_barrier
	ds_read_b128 v[140:143], v0
	ds_read_b128 v[144:147], v0 offset:16
	ds_read_b128 v[148:151], v0 offset:32
	ds_read_b128 v[152:155], v0 offset:48
	ds_read_b128 v[156:159], v0 offset:4096
	ds_read_b128 v[160:163], v0 offset:4112
	ds_read_b128 v[164:167], v0 offset:4128
	ds_read_b128 v[168:171], v0 offset:4144
	s_or_b32 s6, s18, 0x1fe0
	s_add_u32 s60, s6, s30
	s_addc_u32 s61, s19, 0
	s_lshl_b64 s[60:61], s[60:61], 11
	v_lshl_add_u64 v[2:3], v[134:135], 0, s[60:61]
	s_add_u32 s60, s60, 0x2000
	s_addc_u32 s61, s61, 0
	v_lshl_add_u64 v[4:5], v[134:135], 0, s[60:61]
	s_waitcnt lgkmcnt(4)
	v_add_f32_e32 v140, v140, v141
	v_add_f32_e32 v142, v142, v143
	v_add_f32_e32 v144, v144, v145
	v_add_f32_e32 v146, v146, v147
	v_add_f32_e32 v148, v148, v149
	v_add_f32_e32 v150, v150, v151
	v_add_f32_e32 v152, v152, v153
	v_add_f32_e32 v154, v154, v155
	v_add_f32_e32 v140, v140, v142
	v_add_f32_e32 v144, v144, v146
	v_add_f32_e32 v148, v148, v150
	v_add_f32_e32 v152, v152, v154
	v_add_f32_e32 v140, v140, v144
	v_add_f32_e32 v148, v148, v152
	v_add_f32_e32 v140, v140, v148
	v_cvt_pk_bf16_f32 v140, v140, s0
	global_store_short v[2:3], v140, off
	s_waitcnt lgkmcnt(0)
	v_add_f32_e32 v156, v156, v157
	v_add_f32_e32 v158, v158, v159
	v_add_f32_e32 v160, v160, v161
	v_add_f32_e32 v162, v162, v163
	v_add_f32_e32 v164, v164, v165
	v_add_f32_e32 v166, v166, v167
	v_add_f32_e32 v168, v168, v169
	v_add_f32_e32 v170, v170, v171
	v_add_f32_e32 v156, v156, v158
	v_add_f32_e32 v160, v160, v162
	v_add_f32_e32 v164, v164, v166
	v_add_f32_e32 v168, v168, v170
	v_add_f32_e32 v156, v156, v160
	v_add_f32_e32 v164, v164, v168
	v_add_f32_e32 v156, v156, v164
	v_cvt_pk_bf16_f32 v156, v156, s0
	global_store_short v[4:5], v156, off
	s_mov_b64 s[2:3], 0
	s_branch .LBB0_1391

.LBB0_1391:
	s_and_b64 vcc, exec, s[2:3]
	s_cbranch_vccz .LBB0_1397
	s_lshl_b32 s3, s33, 4
	s_lshl_b32 s4, s33, 8
	s_add_i32 s3, s3, 0
	s_add_i32 s4, s4, 0
	s_add_i32 s3, s3, 0x14500
	s_add_i32 s4, s4, 0x15540
	v_and_b32_e32 v0, 3, v24
	v_lshlrev_b32_e32 v1, 2, v24
	s_add_i32 s5, 0, 0x10400
	s_mov_b32 s2, 0
	v_lshl_add_u32 v4, v24, 4, 0
	v_add_u32_e32 v5, s5, v1
	v_lshl_add_u32 v6, v0, 2, s3
	v_add_u32_e32 v7, s4, v1
	v_and_b32_e32 v7, 3, v24
	v_lshrrev_b32_e32 v1, 2, v24
	v_lshlrev_b32_e32 v1, 2, v1
	v_lshl_add_u32 v7, v7, 6, v1
	v_add_u32_e32 v7, s4, v7
	v_mov_b32_e32 v8, 0
	v_mov_b32_e32 v9, 0
	v_mov_b32_e32 v10, 0
	v_mov_b32_e32 v11, 0
.LBB0_1393:
	s_lshl_b32 s3, s2, 5
	s_and_b32 s3, s3, 32
	s_lshl_b32 s4, s3, 10
	v_add_u32_e32 v12, s4, v4
	v_lshl_add_u32 v15, s3, 8, v5
	v_lshl_add_u32 v14, s3, 6, v6
	v_add_u32_e32 v13, s4, v7
	s_mov_b32 s3, 0
	s_waitcnt vmcnt(0) lgkmcnt(0)
	s_barrier
	ds_read_b32 v25, v15
	ds_read_b128 v[0:3], v12
	ds_read_b32 v20, v14
	ds_read_b128 v[28:31], v12 offset:1024
	ds_read_b32 v21, v14 offset:64
	ds_read_b128 v[40:43], v12 offset:2048
	ds_read_b32 v48, v14 offset:128
	ds_read_b32 v23, v15 offset:256
	ds_read_b32 v50, v15 offset:512
	ds_read_b32 v51, v15 offset:768
	s_waitcnt lgkmcnt(7)
	v_mul_f32_dpp v27, v25, v8 quad_perm:[0,0,0,0] row_mask:0xf bank_mask:0xf
	v_fmac_f32_dpp v27, v25, v9 quad_perm:[1,1,1,1] row_mask:0xf bank_mask:0xf
	v_fmac_f32_dpp v27, v25, v10 quad_perm:[2,2,2,2] row_mask:0xf bank_mask:0xf
	v_fmac_f32_dpp v27, v25, v11 quad_perm:[3,3,3,3] row_mask:0xf bank_mask:0xf
	v_mul_f32_dpp v8, v0, v8 quad_perm:[0,0,0,0] row_mask:0xf bank_mask:0xf
	v_mul_f32_dpp v9, v0, v9 quad_perm:[1,1,1,1] row_mask:0xf bank_mask:0xf
	v_add_f32_dpp v32, v27, v27 row_ror:4 row_mask:0xf bank_mask:0xf
	v_mul_f32_dpp v10, v0, v10 quad_perm:[2,2,2,2] row_mask:0xf bank_mask:0xf
	v_mul_f32_dpp v11, v0, v11 quad_perm:[3,3,3,3] row_mask:0xf bank_mask:0xf
	v_add_f32_dpp v33, v32, v32 row_ror:8 row_mask:0xf bank_mask:0xf
	v_add_f32_dpp v34, v32, v32 row_ror:8 row_mask:0xf bank_mask:0xf
	v_fmac_f32_dpp v8, v2, v20 quad_perm:[0,0,0,0] row_mask:0xf bank_mask:0xf
	v_fmac_f32_dpp v9, v2, v20 quad_perm:[1,1,1,1] row_mask:0xf bank_mask:0xf
	v_permlane16_swap_b32_e32 v33, v34
	v_add_f32_e32 v35, v33, v34
	v_add_f32_e32 v36, v33, v34
	v_fmac_f32_dpp v10, v2, v20 quad_perm:[2,2,2,2] row_mask:0xf bank_mask:0xf
	v_fmac_f32_dpp v11, v2, v20 quad_perm:[3,3,3,3] row_mask:0xf bank_mask:0xf
	v_permlane32_swap_b32_e32 v35, v36
	v_add_f32_e32 v17, v35, v36
	s_waitcnt lgkmcnt(0)
.Lscan_grp:
	s_waitcnt lgkmcnt(5)
	v_fmac_f32_dpp v8, v1, v17 quad_perm:[0,0,0,0] row_mask:0xf bank_mask:0xf
	v_fmac_f32_dpp v9, v1, v17 quad_perm:[1,1,1,1] row_mask:0xf bank_mask:0xf
	v_fmac_f32_dpp v10, v1, v17 quad_perm:[2,2,2,2] row_mask:0xf bank_mask:0xf
	v_fmac_f32_dpp v11, v1, v17 quad_perm:[3,3,3,3] row_mask:0xf bank_mask:0xf
	v_mul_f32_dpp v27, v23, v8 quad_perm:[0,0,0,0] row_mask:0xf bank_mask:0xf
	v_mul_f32_dpp v26, v3, v8 quad_perm:[0,0,0,0] row_mask:0xf bank_mask:0xf
	v_fmac_f32_dpp v27, v23, v9 quad_perm:[1,1,1,1] row_mask:0xf bank_mask:0xf
	v_fmac_f32_dpp v26, v3, v9 quad_perm:[1,1,1,1] row_mask:0xf bank_mask:0xf
	v_fmac_f32_dpp v27, v23, v10 quad_perm:[2,2,2,2] row_mask:0xf bank_mask:0xf
	v_fmac_f32_dpp v26, v3, v10 quad_perm:[2,2,2,2] row_mask:0xf bank_mask:0xf
	v_fmac_f32_dpp v27, v23, v11 quad_perm:[3,3,3,3] row_mask:0xf bank_mask:0xf
	v_fmac_f32_dpp v26, v3, v11 quad_perm:[3,3,3,3] row_mask:0xf bank_mask:0xf
	ds_write_b32 v13, v26
	ds_read_b128 v[44:47], v12 offset:3072
	ds_read_b32 v49, v14 offset:192
	ds_read_b32 v22, v15 offset:1024
	v_mul_f32_dpp v8, v28, v8 quad_perm:[0,0,0,0] row_mask:0xf bank_mask:0xf
	v_add_f32_dpp v32, v27, v27 row_ror:4 row_mask:0xf bank_mask:0xf
	v_mul_f32_dpp v9, v28, v9 quad_perm:[1,1,1,1] row_mask:0xf bank_mask:0xf
	v_mul_f32_dpp v10, v28, v10 quad_perm:[2,2,2,2] row_mask:0xf bank_mask:0xf
	v_add_f32_dpp v33, v32, v32 row_ror:8 row_mask:0xf bank_mask:0xf
	v_add_f32_dpp v34, v32, v32 row_ror:8 row_mask:0xf bank_mask:0xf
	v_mul_f32_dpp v11, v28, v11 quad_perm:[3,3,3,3] row_mask:0xf bank_mask:0xf
	v_fmac_f32_dpp v8, v30, v21 quad_perm:[0,0,0,0] row_mask:0xf bank_mask:0xf
	v_permlane16_swap_b32_e32 v33, v34
	v_add_f32_e32 v35, v33, v34
	v_add_f32_e32 v36, v33, v34
	v_fmac_f32_dpp v9, v30, v21 quad_perm:[1,1,1,1] row_mask:0xf bank_mask:0xf
	v_fmac_f32_dpp v10, v30, v21 quad_perm:[2,2,2,2] row_mask:0xf bank_mask:0xf
	v_permlane32_swap_b32_e32 v35, v36
	v_add_f32_e32 v17, v35, v36
	v_fmac_f32_dpp v11, v30, v21 quad_perm:[3,3,3,3] row_mask:0xf bank_mask:0xf
	s_waitcnt lgkmcnt(5)
	v_fmac_f32_dpp v8, v29, v17 quad_perm:[0,0,0,0] row_mask:0xf bank_mask:0xf
	v_fmac_f32_dpp v9, v29, v17 quad_perm:[1,1,1,1] row_mask:0xf bank_mask:0xf
	v_fmac_f32_dpp v10, v29, v17 quad_perm:[2,2,2,2] row_mask:0xf bank_mask:0xf
	v_fmac_f32_dpp v11, v29, v17 quad_perm:[3,3,3,3] row_mask:0xf bank_mask:0xf
	v_mul_f32_dpp v27, v50, v8 quad_perm:[0,0,0,0] row_mask:0xf bank_mask:0xf
	v_mul_f32_dpp v26, v31, v8 quad_perm:[0,0,0,0] row_mask:0xf bank_mask:0xf
	v_fmac_f32_dpp v27, v50, v9 quad_perm:[1,1,1,1] row_mask:0xf bank_mask:0xf
	v_fmac_f32_dpp v26, v31, v9 quad_perm:[1,1,1,1] row_mask:0xf bank_mask:0xf
	v_fmac_f32_dpp v27, v50, v10 quad_perm:[2,2,2,2] row_mask:0xf bank_mask:0xf
	v_fmac_f32_dpp v26, v31, v10 quad_perm:[2,2,2,2] row_mask:0xf bank_mask:0xf
	v_fmac_f32_dpp v27, v50, v11 quad_perm:[3,3,3,3] row_mask:0xf bank_mask:0xf
	v_fmac_f32_dpp v26, v31, v11 quad_perm:[3,3,3,3] row_mask:0xf bank_mask:0xf
	ds_write_b32 v13, v26 offset:1024
	ds_read_b128 v[0:3], v12 offset:4096
	ds_read_b32 v20, v14 offset:256
	ds_read_b32 v23, v15 offset:1280
	v_mul_f32_dpp v8, v40, v8 quad_perm:[0,0,0,0] row_mask:0xf bank_mask:0xf
	v_add_f32_dpp v32, v27, v27 row_ror:4 row_mask:0xf bank_mask:0xf
	v_mul_f32_dpp v9, v40, v9 quad_perm:[1,1,1,1] row_mask:0xf bank_mask:0xf
	v_mul_f32_dpp v10, v40, v10 quad_perm:[2,2,2,2] row_mask:0xf bank_mask:0xf
	v_add_f32_dpp v33, v32, v32 row_ror:8 row_mask:0xf bank_mask:0xf
	v_add_f32_dpp v34, v32, v32 row_ror:8 row_mask:0xf bank_mask:0xf
	v_mul_f32_dpp v11, v40, v11 quad_perm:[3,3,3,3] row_mask:0xf bank_mask:0xf
	v_fmac_f32_dpp v8, v42, v48 quad_perm:[0,0,0,0] row_mask:0xf bank_mask:0xf
	v_permlane16_swap_b32_e32 v33, v34
	v_add_f32_e32 v35, v33, v34
	v_add_f32_e32 v36, v33, v34
	v_fmac_f32_dpp v9, v42, v48 quad_perm:[1,1,1,1] row_mask:0xf bank_mask:0xf
	v_fmac_f32_dpp v10, v42, v48 quad_perm:[2,2,2,2] row_mask:0xf bank_mask:0xf
	v_permlane32_swap_b32_e32 v35, v36
	v_add_f32_e32 v17, v35, v36
	v_fmac_f32_dpp v11, v42, v48 quad_perm:[3,3,3,3] row_mask:0xf bank_mask:0xf
	s_waitcnt lgkmcnt(5)
	v_fmac_f32_dpp v8, v41, v17 quad_perm:[0,0,0,0] row_mask:0xf bank_mask:0xf
	v_fmac_f32_dpp v9, v41, v17 quad_perm:[1,1,1,1] row_mask:0xf bank_mask:0xf
	v_fmac_f32_dpp v10, v41, v17 quad_perm:[2,2,2,2] row_mask:0xf bank_mask:0xf
	v_fmac_f32_dpp v11, v41, v17 quad_perm:[3,3,3,3] row_mask:0xf bank_mask:0xf
	v_mul_f32_dpp v27, v51, v8 quad_perm:[0,0,0,0] row_mask:0xf bank_mask:0xf
	v_mul_f32_dpp v26, v43, v8 quad_perm:[0,0,0,0] row_mask:0xf bank_mask:0xf
	v_fmac_f32_dpp v27, v51, v9 quad_perm:[1,1,1,1] row_mask:0xf bank_mask:0xf
	v_fmac_f32_dpp v26, v43, v9 quad_perm:[1,1,1,1] row_mask:0xf bank_mask:0xf
	v_fmac_f32_dpp v27, v51, v10 quad_perm:[2,2,2,2] row_mask:0xf bank_mask:0xf
	v_fmac_f32_dpp v26, v43, v10 quad_perm:[2,2,2,2] row_mask:0xf bank_mask:0xf
	v_fmac_f32_dpp v27, v51, v11 quad_perm:[3,3,3,3] row_mask:0xf bank_mask:0xf
	v_fmac_f32_dpp v26, v43, v11 quad_perm:[3,3,3,3] row_mask:0xf bank_mask:0xf
	ds_write_b32 v13, v26 offset:2048
	ds_read_b128 v[28:31], v12 offset:5120
	ds_read_b32 v21, v14 offset:320
	ds_read_b32 v50, v15 offset:1536
	v_mul_f32_dpp v8, v44, v8 quad_perm:[0,0,0,0] row_mask:0xf bank_mask:0xf
	v_add_f32_dpp v32, v27, v27 row_ror:4 row_mask:0xf bank_mask:0xf
	v_mul_f32_dpp v9, v44, v9 quad_perm:[1,1,1,1] row_mask:0xf bank_mask:0xf
	v_mul_f32_dpp v10, v44, v10 quad_perm:[2,2,2,2] row_mask:0xf bank_mask:0xf
	v_add_f32_dpp v33, v32, v32 row_ror:8 row_mask:0xf bank_mask:0xf
	v_add_f32_dpp v34, v32, v32 row_ror:8 row_mask:0xf bank_mask:0xf
	v_mul_f32_dpp v11, v44, v11 quad_perm:[3,3,3,3] row_mask:0xf bank_mask:0xf
	v_fmac_f32_dpp v8, v46, v49 quad_perm:[0,0,0,0] row_mask:0xf bank_mask:0xf
	v_permlane16_swap_b32_e32 v33, v34
	v_add_f32_e32 v35, v33, v34
	v_add_f32_e32 v36, v33, v34
	v_fmac_f32_dpp v9, v46, v49 quad_perm:[1,1,1,1] row_mask:0xf bank_mask:0xf
	v_fmac_f32_dpp v10, v46, v49 quad_perm:[2,2,2,2] row_mask:0xf bank_mask:0xf
	v_permlane32_swap_b32_e32 v35, v36
	v_add_f32_e32 v17, v35, v36
	v_fmac_f32_dpp v11, v46, v49 quad_perm:[3,3,3,3] row_mask:0xf bank_mask:0xf
	s_waitcnt lgkmcnt(5)
	v_fmac_f32_dpp v8, v45, v17 quad_perm:[0,0,0,0] row_mask:0xf bank_mask:0xf
	v_fmac_f32_dpp v9, v45, v17 quad_perm:[1,1,1,1] row_mask:0xf bank_mask:0xf
	v_fmac_f32_dpp v10, v45, v17 quad_perm:[2,2,2,2] row_mask:0xf bank_mask:0xf
	v_fmac_f32_dpp v11, v45, v17 quad_perm:[3,3,3,3] row_mask:0xf bank_mask:0xf
	v_mul_f32_dpp v27, v22, v8 quad_perm:[0,0,0,0] row_mask:0xf bank_mask:0xf
	v_mul_f32_dpp v26, v47, v8 quad_perm:[0,0,0,0] row_mask:0xf bank_mask:0xf
	v_fmac_f32_dpp v27, v22, v9 quad_perm:[1,1,1,1] row_mask:0xf bank_mask:0xf
	v_fmac_f32_dpp v26, v47, v9 quad_perm:[1,1,1,1] row_mask:0xf bank_mask:0xf
	v_fmac_f32_dpp v27, v22, v10 quad_perm:[2,2,2,2] row_mask:0xf bank_mask:0xf
	v_fmac_f32_dpp v26, v47, v10 quad_perm:[2,2,2,2] row_mask:0xf bank_mask:0xf
	v_fmac_f32_dpp v27, v22, v11 quad_perm:[3,3,3,3] row_mask:0xf bank_mask:0xf
	v_fmac_f32_dpp v26, v47, v11 quad_perm:[3,3,3,3] row_mask:0xf bank_mask:0xf
	ds_write_b32 v13, v26 offset:3072
	ds_read_b128 v[40:43], v12 offset:6144
	ds_read_b32 v48, v14 offset:384
	ds_read_b32 v51, v15 offset:1792
	v_mul_f32_dpp v8, v0, v8 quad_perm:[0,0,0,0] row_mask:0xf bank_mask:0xf
	v_add_f32_dpp v32, v27, v27 row_ror:4 row_mask:0xf bank_mask:0xf
	v_mul_f32_dpp v9, v0, v9 quad_perm:[1,1,1,1] row_mask:0xf bank_mask:0xf
	v_mul_f32_dpp v10, v0, v10 quad_perm:[2,2,2,2] row_mask:0xf bank_mask:0xf
	v_add_f32_dpp v33, v32, v32 row_ror:8 row_mask:0xf bank_mask:0xf
	v_add_f32_dpp v34, v32, v32 row_ror:8 row_mask:0xf bank_mask:0xf
	v_mul_f32_dpp v11, v0, v11 quad_perm:[3,3,3,3] row_mask:0xf bank_mask:0xf
	v_fmac_f32_dpp v8, v2, v20 quad_perm:[0,0,0,0] row_mask:0xf bank_mask:0xf
	v_permlane16_swap_b32_e32 v33, v34
	v_add_f32_e32 v35, v33, v34
	v_add_f32_e32 v36, v33, v34
	v_fmac_f32_dpp v9, v2, v20 quad_perm:[1,1,1,1] row_mask:0xf bank_mask:0xf
	v_fmac_f32_dpp v10, v2, v20 quad_perm:[2,2,2,2] row_mask:0xf bank_mask:0xf
	v_permlane32_swap_b32_e32 v35, v36
	v_add_f32_e32 v17, v35, v36
	v_fmac_f32_dpp v11, v2, v20 quad_perm:[3,3,3,3] row_mask:0xf bank_mask:0xf
	s_waitcnt lgkmcnt(5)
	v_fmac_f32_dpp v8, v1, v17 quad_perm:[0,0,0,0] row_mask:0xf bank_mask:0xf
	v_fmac_f32_dpp v9, v1, v17 quad_perm:[1,1,1,1] row_mask:0xf bank_mask:0xf
	v_fmac_f32_dpp v10, v1, v17 quad_perm:[2,2,2,2] row_mask:0xf bank_mask:0xf
	v_fmac_f32_dpp v11, v1, v17 quad_perm:[3,3,3,3] row_mask:0xf bank_mask:0xf
	v_mul_f32_dpp v27, v23, v8 quad_perm:[0,0,0,0] row_mask:0xf bank_mask:0xf
	v_mul_f32_dpp v26, v3, v8 quad_perm:[0,0,0,0] row_mask:0xf bank_mask:0xf
	v_fmac_f32_dpp v27, v23, v9 quad_perm:[1,1,1,1] row_mask:0xf bank_mask:0xf
	v_fmac_f32_dpp v26, v3, v9 quad_perm:[1,1,1,1] row_mask:0xf bank_mask:0xf
	v_fmac_f32_dpp v27, v23, v10 quad_perm:[2,2,2,2] row_mask:0xf bank_mask:0xf
	v_fmac_f32_dpp v26, v3, v10 quad_perm:[2,2,2,2] row_mask:0xf bank_mask:0xf
	v_fmac_f32_dpp v27, v23, v11 quad_perm:[3,3,3,3] row_mask:0xf bank_mask:0xf
	v_fmac_f32_dpp v26, v3, v11 quad_perm:[3,3,3,3] row_mask:0xf bank_mask:0xf
	ds_write_b32 v13, v26 offset:4096
	ds_read_b128 v[44:47], v12 offset:7168
	ds_read_b32 v49, v14 offset:448
	ds_read_b32 v22, v15 offset:2048
	v_mul_f32_dpp v8, v28, v8 quad_perm:[0,0,0,0] row_mask:0xf bank_mask:0xf
	v_add_f32_dpp v32, v27, v27 row_ror:4 row_mask:0xf bank_mask:0xf
	v_mul_f32_dpp v9, v28, v9 quad_perm:[1,1,1,1] row_mask:0xf bank_mask:0xf
	v_mul_f32_dpp v10, v28, v10 quad_perm:[2,2,2,2] row_mask:0xf bank_mask:0xf
	v_add_f32_dpp v33, v32, v32 row_ror:8 row_mask:0xf bank_mask:0xf
	v_add_f32_dpp v34, v32, v32 row_ror:8 row_mask:0xf bank_mask:0xf
	v_mul_f32_dpp v11, v28, v11 quad_perm:[3,3,3,3] row_mask:0xf bank_mask:0xf
	v_fmac_f32_dpp v8, v30, v21 quad_perm:[0,0,0,0] row_mask:0xf bank_mask:0xf
	v_permlane16_swap_b32_e32 v33, v34
	v_add_f32_e32 v35, v33, v34
	v_add_f32_e32 v36, v33, v34
	v_fmac_f32_dpp v9, v30, v21 quad_perm:[1,1,1,1] row_mask:0xf bank_mask:0xf
	v_fmac_f32_dpp v10, v30, v21 quad_perm:[2,2,2,2] row_mask:0xf bank_mask:0xf
	v_permlane32_swap_b32_e32 v35, v36
	v_add_f32_e32 v17, v35, v36
	v_fmac_f32_dpp v11, v30, v21 quad_perm:[3,3,3,3] row_mask:0xf bank_mask:0xf
	s_waitcnt lgkmcnt(5)
	v_fmac_f32_dpp v8, v29, v17 quad_perm:[0,0,0,0] row_mask:0xf bank_mask:0xf
	v_fmac_f32_dpp v9, v29, v17 quad_perm:[1,1,1,1] row_mask:0xf bank_mask:0xf
	v_fmac_f32_dpp v10, v29, v17 quad_perm:[2,2,2,2] row_mask:0xf bank_mask:0xf
	v_fmac_f32_dpp v11, v29, v17 quad_perm:[3,3,3,3] row_mask:0xf bank_mask:0xf
	v_mul_f32_dpp v27, v50, v8 quad_perm:[0,0,0,0] row_mask:0xf bank_mask:0xf
	v_mul_f32_dpp v26, v31, v8 quad_perm:[0,0,0,0] row_mask:0xf bank_mask:0xf
	v_fmac_f32_dpp v27, v50, v9 quad_perm:[1,1,1,1] row_mask:0xf bank_mask:0xf
	v_fmac_f32_dpp v26, v31, v9 quad_perm:[1,1,1,1] row_mask:0xf bank_mask:0xf
	v_fmac_f32_dpp v27, v50, v10 quad_perm:[2,2,2,2] row_mask:0xf bank_mask:0xf
	v_fmac_f32_dpp v26, v31, v10 quad_perm:[2,2,2,2] row_mask:0xf bank_mask:0xf
	v_fmac_f32_dpp v27, v50, v11 quad_perm:[3,3,3,3] row_mask:0xf bank_mask:0xf
	v_fmac_f32_dpp v26, v31, v11 quad_perm:[3,3,3,3] row_mask:0xf bank_mask:0xf
	ds_write_b32 v13, v26 offset:5120
	ds_read_b128 v[0:3], v12 offset:8192
	ds_read_b32 v20, v14 offset:512
	ds_read_b32 v23, v15 offset:2304
	v_mul_f32_dpp v8, v40, v8 quad_perm:[0,0,0,0] row_mask:0xf bank_mask:0xf
	v_add_f32_dpp v32, v27, v27 row_ror:4 row_mask:0xf bank_mask:0xf
	v_mul_f32_dpp v9, v40, v9 quad_perm:[1,1,1,1] row_mask:0xf bank_mask:0xf
	v_mul_f32_dpp v10, v40, v10 quad_perm:[2,2,2,2] row_mask:0xf bank_mask:0xf
	v_add_f32_dpp v33, v32, v32 row_ror:8 row_mask:0xf bank_mask:0xf
	v_add_f32_dpp v34, v32, v32 row_ror:8 row_mask:0xf bank_mask:0xf
	v_mul_f32_dpp v11, v40, v11 quad_perm:[3,3,3,3] row_mask:0xf bank_mask:0xf
	v_fmac_f32_dpp v8, v42, v48 quad_perm:[0,0,0,0] row_mask:0xf bank_mask:0xf
	v_permlane16_swap_b32_e32 v33, v34
	v_add_f32_e32 v35, v33, v34
	v_add_f32_e32 v36, v33, v34
	v_fmac_f32_dpp v9, v42, v48 quad_perm:[1,1,1,1] row_mask:0xf bank_mask:0xf
	v_fmac_f32_dpp v10, v42, v48 quad_perm:[2,2,2,2] row_mask:0xf bank_mask:0xf
	v_permlane32_swap_b32_e32 v35, v36
	v_add_f32_e32 v17, v35, v36
	v_fmac_f32_dpp v11, v42, v48 quad_perm:[3,3,3,3] row_mask:0xf bank_mask:0xf
	s_waitcnt lgkmcnt(5)
	v_fmac_f32_dpp v8, v41, v17 quad_perm:[0,0,0,0] row_mask:0xf bank_mask:0xf
	v_fmac_f32_dpp v9, v41, v17 quad_perm:[1,1,1,1] row_mask:0xf bank_mask:0xf
	v_fmac_f32_dpp v10, v41, v17 quad_perm:[2,2,2,2] row_mask:0xf bank_mask:0xf
	v_fmac_f32_dpp v11, v41, v17 quad_perm:[3,3,3,3] row_mask:0xf bank_mask:0xf
	v_mul_f32_dpp v27, v51, v8 quad_perm:[0,0,0,0] row_mask:0xf bank_mask:0xf
	v_mul_f32_dpp v26, v43, v8 quad_perm:[0,0,0,0] row_mask:0xf bank_mask:0xf
	v_fmac_f32_dpp v27, v51, v9 quad_perm:[1,1,1,1] row_mask:0xf bank_mask:0xf
	v_fmac_f32_dpp v26, v43, v9 quad_perm:[1,1,1,1] row_mask:0xf bank_mask:0xf
	v_fmac_f32_dpp v27, v51, v10 quad_perm:[2,2,2,2] row_mask:0xf bank_mask:0xf
	v_fmac_f32_dpp v26, v43, v10 quad_perm:[2,2,2,2] row_mask:0xf bank_mask:0xf
	v_fmac_f32_dpp v27, v51, v11 quad_perm:[3,3,3,3] row_mask:0xf bank_mask:0xf
	v_fmac_f32_dpp v26, v43, v11 quad_perm:[3,3,3,3] row_mask:0xf bank_mask:0xf
	ds_write_b32 v13, v26 offset:6144
	ds_read_b128 v[28:31], v12 offset:9216
	ds_read_b32 v21, v14 offset:576
	ds_read_b32 v50, v15 offset:2560
	v_mul_f32_dpp v8, v44, v8 quad_perm:[0,0,0,0] row_mask:0xf bank_mask:0xf
	v_add_f32_dpp v32, v27, v27 row_ror:4 row_mask:0xf bank_mask:0xf
	v_mul_f32_dpp v9, v44, v9 quad_perm:[1,1,1,1] row_mask:0xf bank_mask:0xf
	v_mul_f32_dpp v10, v44, v10 quad_perm:[2,2,2,2] row_mask:0xf bank_mask:0xf
	v_add_f32_dpp v33, v32, v32 row_ror:8 row_mask:0xf bank_mask:0xf
	v_add_f32_dpp v34, v32, v32 row_ror:8 row_mask:0xf bank_mask:0xf
	v_mul_f32_dpp v11, v44, v11 quad_perm:[3,3,3,3] row_mask:0xf bank_mask:0xf
	v_fmac_f32_dpp v8, v46, v49 quad_perm:[0,0,0,0] row_mask:0xf bank_mask:0xf
	v_permlane16_swap_b32_e32 v33, v34
	v_add_f32_e32 v35, v33, v34
	v_add_f32_e32 v36, v33, v34
	v_fmac_f32_dpp v9, v46, v49 quad_perm:[1,1,1,1] row_mask:0xf bank_mask:0xf
	v_fmac_f32_dpp v10, v46, v49 quad_perm:[2,2,2,2] row_mask:0xf bank_mask:0xf
	v_permlane32_swap_b32_e32 v35, v36
	v_add_f32_e32 v17, v35, v36
	v_fmac_f32_dpp v11, v46, v49 quad_perm:[3,3,3,3] row_mask:0xf bank_mask:0xf
	s_waitcnt lgkmcnt(5)
	v_fmac_f32_dpp v8, v45, v17 quad_perm:[0,0,0,0] row_mask:0xf bank_mask:0xf
	v_fmac_f32_dpp v9, v45, v17 quad_perm:[1,1,1,1] row_mask:0xf bank_mask:0xf
	v_fmac_f32_dpp v10, v45, v17 quad_perm:[2,2,2,2] row_mask:0xf bank_mask:0xf
	v_fmac_f32_dpp v11, v45, v17 quad_perm:[3,3,3,3] row_mask:0xf bank_mask:0xf
	s_cmp_eq_u32 s3, 3
	v_mul_f32_dpp v27, v22, v8 quad_perm:[0,0,0,0] row_mask:0xf bank_mask:0xf
	v_mul_f32_dpp v26, v47, v8 quad_perm:[0,0,0,0] row_mask:0xf bank_mask:0xf
	v_fmac_f32_dpp v27, v22, v9 quad_perm:[1,1,1,1] row_mask:0xf bank_mask:0xf
	v_fmac_f32_dpp v26, v47, v9 quad_perm:[1,1,1,1] row_mask:0xf bank_mask:0xf
	v_fmac_f32_dpp v27, v22, v10 quad_perm:[2,2,2,2] row_mask:0xf bank_mask:0xf
	v_fmac_f32_dpp v26, v47, v10 quad_perm:[2,2,2,2] row_mask:0xf bank_mask:0xf
	v_fmac_f32_dpp v27, v22, v11 quad_perm:[3,3,3,3] row_mask:0xf bank_mask:0xf
	v_fmac_f32_dpp v26, v47, v11 quad_perm:[3,3,3,3] row_mask:0xf bank_mask:0xf
	ds_write_b32 v13, v26 offset:7168
	s_cbranch_scc1 .Lscan_blk_end
	ds_read_b128 v[40:43], v12 offset:10240
	ds_read_b32 v48, v14 offset:640
	ds_read_b32 v51, v15 offset:2816
	v_mul_f32_dpp v8, v0, v8 quad_perm:[0,0,0,0] row_mask:0xf bank_mask:0xf
	v_add_f32_dpp v32, v27, v27 row_ror:4 row_mask:0xf bank_mask:0xf
	v_mul_f32_dpp v9, v0, v9 quad_perm:[1,1,1,1] row_mask:0xf bank_mask:0xf
	v_mul_f32_dpp v10, v0, v10 quad_perm:[2,2,2,2] row_mask:0xf bank_mask:0xf
	v_add_f32_dpp v33, v32, v32 row_ror:8 row_mask:0xf bank_mask:0xf
	v_add_f32_dpp v34, v32, v32 row_ror:8 row_mask:0xf bank_mask:0xf
	v_mul_f32_dpp v11, v0, v11 quad_perm:[3,3,3,3] row_mask:0xf bank_mask:0xf
	v_fmac_f32_dpp v8, v2, v20 quad_perm:[0,0,0,0] row_mask:0xf bank_mask:0xf
	v_permlane16_swap_b32_e32 v33, v34
	v_add_f32_e32 v35, v33, v34
	v_add_f32_e32 v36, v33, v34
	v_fmac_f32_dpp v9, v2, v20 quad_perm:[1,1,1,1] row_mask:0xf bank_mask:0xf
	v_fmac_f32_dpp v10, v2, v20 quad_perm:[2,2,2,2] row_mask:0xf bank_mask:0xf
	v_permlane32_swap_b32_e32 v35, v36
	v_add_f32_e32 v17, v35, v36
	v_fmac_f32_dpp v11, v2, v20 quad_perm:[3,3,3,3] row_mask:0xf bank_mask:0xf
	v_add_u32_e32 v12, 0x2000, v12
	v_add_u32_e32 v13, 0x2000, v13
	v_add_u32_e32 v14, 0x200, v14
	v_add_u32_e32 v15, 0x800, v15
	s_add_i32 s3, s3, 1
	s_branch .Lscan_grp
